# residual-add epilogues of P7/P10/P12: second half's 8 residual loads issued together with the first half's (free VGPR quads, v248-255 enabled); on top of mnk + saddr + P13 gain hoist
# baseline (speedup 1.0000x reference)
.LBB0_2343:
	s_lshl_b32 s42, s3, 8
	v_lshl_or_b32 v174, s33, 8, v185
	v_add_u32_e32 v178, s42, v162
	v_ashrrev_i32_e32 v175, 31, v174
	v_lshlrev_b64 v[202:203], 1, v[174:175]
	v_ashrrev_i32_e32 v179, 31, v178
	v_lshl_add_u64 v[176:177], s[16:17], 0, v[202:203]
	v_lshlrev_b64 v[204:205], 13, v[178:179]
	v_lshl_add_u64 v[130:131], v[176:177], 0, v[204:205]
	global_load_dwordx4 v[194:197], v[130:131], off
	global_load_dwordx4 v[198:201], v[130:131], off offset:256
	v_or_b32_e32 v188, 16, v178
	v_or_b32_e32 v186, 32, v178
	v_or_b32_e32 v180, 48, v178
	v_ashrrev_i32_e32 v189, 31, v188
	v_ashrrev_i32_e32 v187, 31, v186
	v_ashrrev_i32_e32 v181, 31, v180
	v_lshlrev_b64 v[130:131], 13, v[188:189]
	v_lshlrev_b64 v[132:133], 13, v[186:187]
	v_lshlrev_b64 v[134:135], 13, v[180:181]
	v_lshl_add_u64 v[130:131], v[176:177], 0, v[130:131]
	v_lshl_add_u64 v[132:133], v[176:177], 0, v[132:133]
	v_lshl_add_u64 v[206:207], v[176:177], 0, v[134:135]
	global_load_dwordx4 v[150:153], v[130:131], off
	global_load_dwordx4 v[146:149], v[130:131], off offset:256
	global_load_dwordx4 v[142:145], v[132:133], off
	global_load_dwordx4 v[138:141], v[132:133], off offset:256
	global_load_dwordx4 v[134:137], v[206:207], off
	s_nop 0
	global_load_dwordx4 v[130:133], v[206:207], off offset:256
	v_add_u32_e32 v246, 0x80, v178
	v_ashrrev_i32_e32 v247, 31, v246
	v_lshlrev_b64 v[248:249], 13, v[246:247]
	v_lshl_add_u64 v[250:251], v[176:177], 0, v[248:249]
	global_load_dwordx4 v[212:215], v[250:251], off
	global_load_dwordx4 v[216:219], v[250:251], off offset:256
	v_add_u32_e32 v246, 0x90, v178
	v_ashrrev_i32_e32 v247, 31, v246
	v_lshlrev_b64 v[248:249], 13, v[246:247]
	v_lshl_add_u64 v[252:253], v[176:177], 0, v[248:249]
	global_load_dwordx4 v[220:223], v[252:253], off
	global_load_dwordx4 v[224:227], v[252:253], off offset:256
	v_add_u32_e32 v246, 0xa0, v178
	v_ashrrev_i32_e32 v247, 31, v246
	v_lshlrev_b64 v[248:249], 13, v[246:247]
	v_lshl_add_u64 v[254:255], v[176:177], 0, v[248:249]
	global_load_dwordx4 v[228:231], v[254:255], off
	global_load_dwordx4 v[232:235], v[254:255], off offset:256
	v_add_u32_e32 v246, 0xb0, v178
	v_ashrrev_i32_e32 v247, 31, v246
	v_lshlrev_b64 v[248:249], 13, v[246:247]
	v_lshl_add_u64 v[250:251], v[176:177], 0, v[248:249]
	global_load_dwordx4 v[236:239], v[250:251], off
	global_load_dwordx4 v[240:243], v[250:251], off offset:256
	v_and_b32_e32 v193, 64, v192
	v_xor_b32_e32 v179, 16, v192
	v_add_u32_e32 v193, 64, v193
	v_xor_b32_e32 v206, 32, v192
	v_cmp_lt_i32_e32 vcc, v179, v193
	v_lshl_add_u64 v[204:205], s[16:17], 0, v[204:205]
	v_lshl_add_u64 v[202:203], v[204:205], 0, v[202:203]
	v_cndmask_b32_e32 v179, v192, v179, vcc
	v_cmp_lt_i32_e32 vcc, v206, v193
	v_lshlrev_b32_e32 v179, 2, v179
	s_waitcnt vmcnt(8)
	v_lshlrev_b32_e32 v204, 16, v194
	v_and_b32_e32 v205, 0xffff0000, v194
	v_lshlrev_b32_e32 v194, 16, v195
	v_and_b32_e32 v195, 0xffff0000, v195
	v_lshlrev_b32_e32 v208, 16, v198
	v_and_b32_e32 v209, 0xffff0000, v198
	v_lshlrev_b32_e32 v198, 16, v199
	v_and_b32_e32 v199, 0xffff0000, v199
	v_cndmask_b32_e32 v193, v192, v206, vcc
	v_lshlrev_b32_e32 v206, 16, v196
	v_and_b32_e32 v207, 0xffff0000, v196
	v_lshlrev_b32_e32 v196, 16, v197
	v_and_b32_e32 v197, 0xffff0000, v197
	v_lshlrev_b32_e32 v210, 16, v200
	v_and_b32_e32 v211, 0xffff0000, v200
	v_lshlrev_b32_e32 v200, 16, v201
	v_and_b32_e32 v201, 0xffff0000, v201
	v_pk_add_f32 v[128:129], v[128:129], v[194:195]
	v_pk_add_f32 v[126:127], v[126:127], v[204:205]
	v_pk_add_f32 v[120:121], v[120:121], v[198:199]
	v_pk_add_f32 v[118:119], v[118:119], v[208:209]
	v_pk_add_f32 v[124:125], v[124:125], v[196:197]
	v_pk_add_f32 v[122:123], v[122:123], v[206:207]
	v_pk_add_f32 v[194:195], v[116:117], v[200:201]
	v_pk_add_f32 v[196:197], v[114:115], v[210:211]
	v_mul_f32_e32 v116, v127, v127
	v_mul_f32_e32 v117, v129, v129
	v_mul_f32_e32 v198, v119, v119
	v_mul_f32_e32 v199, v121, v121
	v_cvt_pk_bf16_f32 v114, v126, v127
	v_mul_f32_e32 v127, v123, v123
	v_mul_f32_e32 v200, v197, v197
	v_fmac_f32_e32 v116, v126, v126
	v_fmac_f32_e32 v117, v128, v128
	v_fmac_f32_e32 v198, v118, v118
	v_fmac_f32_e32 v199, v120, v120
	v_cvt_pk_bf16_f32 v115, v128, v129
	v_mul_f32_e32 v129, v125, v125
	v_mul_f32_e32 v201, v195, v195
	v_fmac_f32_e32 v127, v122, v122
	v_fmac_f32_e32 v200, v196, v196
	v_add_f32_e32 v116, v116, v117
	v_add_f32_e32 v117, v198, v199
	v_fmac_f32_e32 v129, v124, v124
	v_fmac_f32_e32 v201, v194, v194
	v_add_f32_e32 v116, v127, v116
	v_add_f32_e32 v117, v200, v117
	v_add_f32_e32 v116, v129, v116
	v_add_f32_e32 v117, v201, v117
	v_add_f32_e32 v126, v116, v117
	ds_bpermute_b32 v127, v179, v126
	v_cvt_pk_bf16_f32 v116, v122, v123
	v_cvt_pk_bf16_f32 v117, v124, v125
	global_store_dwordx4 v[202:203], v[114:117], off
	v_cvt_pk_bf16_f32 v118, v118, v119
	v_cvt_pk_bf16_f32 v119, v120, v121
	v_cvt_pk_bf16_f32 v120, v196, v197
	v_cvt_pk_bf16_f32 v121, v194, v195
	global_store_dwordx4 v[202:203], v[118:121], off offset:256
	s_waitcnt lgkmcnt(0)
	v_add_f32_e32 v115, v126, v127
	v_lshlrev_b32_e32 v114, 2, v193
	ds_bpermute_b32 v116, v114, v115
	s_and_saveexec_b64 s[40:41], s[4:5]
	s_cbranch_execz .LBB0_2345
	s_lshl_b32 s12, s3, 4
	s_add_i32 s44, s12, s33
	s_ashr_i32 s45, s44, 31
	s_lshl_b64 s[44:45], s[44:45], 12
	s_waitcnt lgkmcnt(0)
	v_add_f32_e32 v115, v115, v116
	v_lshl_add_u64 v[116:117], v[164:165], 0, s[44:45]
	global_store_dword v[116:117], v115, off

.LBB0_2351:
	s_or_b64 exec, exec, s[40:41]
	v_add_u32_e32 v96, 0x80, v178
	v_ashrrev_i32_e32 v97, 31, v96
	v_lshlrev_b64 v[106:107], 13, v[96:97]
	s_waitcnt lgkmcnt(0)
	v_lshl_add_u64 v[66:67], v[176:177], 0, v[106:107]
	v_add_u32_e32 v94, 0x90, v178
	v_add_u32_e32 v92, 0xa0, v178
	v_add_u32_e32 v90, 0xb0, v178
	v_ashrrev_i32_e32 v95, 31, v94
	v_ashrrev_i32_e32 v93, 31, v92
	v_ashrrev_i32_e32 v91, 31, v90
	v_lshlrev_b64 v[66:67], 13, v[94:95]
	v_lshlrev_b64 v[68:69], 13, v[92:93]
	v_lshlrev_b64 v[70:71], 13, v[90:91]
	v_lshl_add_u64 v[66:67], v[176:177], 0, v[66:67]
	v_lshl_add_u64 v[68:69], v[176:177], 0, v[68:69]
	v_lshl_add_u64 v[108:109], v[176:177], 0, v[70:71]
	s_waitcnt vmcnt(8)
	v_lshlrev_b32_e32 v108, 16, v212
	v_and_b32_e32 v109, 0xffff0000, v212
	v_lshlrev_b32_e32 v98, 16, v213
	v_and_b32_e32 v99, 0xffff0000, v213
	v_lshlrev_b32_e32 v112, 16, v216
	v_and_b32_e32 v113, 0xffff0000, v216
	v_lshlrev_b32_e32 v102, 16, v217
	v_and_b32_e32 v103, 0xffff0000, v217
	v_lshlrev_b32_e32 v110, 16, v214
	v_and_b32_e32 v111, 0xffff0000, v214
	v_lshlrev_b32_e32 v100, 16, v215
	v_and_b32_e32 v101, 0xffff0000, v215
	v_lshlrev_b32_e32 v116, 16, v218
	v_and_b32_e32 v117, 0xffff0000, v218
	v_pk_add_f32 v[64:65], v[64:65], v[98:99]
	v_pk_add_f32 v[62:63], v[62:63], v[108:109]
	v_pk_add_f32 v[56:57], v[56:57], v[102:103]
	v_pk_add_f32 v[54:55], v[54:55], v[112:113]
	v_lshlrev_b32_e32 v104, 16, v219
	v_and_b32_e32 v105, 0xffff0000, v219
	v_pk_add_f32 v[60:61], v[60:61], v[100:101]
	v_pk_add_f32 v[58:59], v[58:59], v[110:111]
	v_pk_add_f32 v[100:101], v[50:51], v[116:117]
	v_cvt_pk_bf16_f32 v50, v62, v63
	v_cvt_pk_bf16_f32 v51, v64, v65
	v_mul_f32_e32 v63, v63, v63
	v_mul_f32_e32 v65, v65, v65
	v_mul_f32_e32 v97, v55, v55
	v_mul_f32_e32 v102, v57, v57
	v_pk_add_f32 v[98:99], v[52:53], v[104:105]
	v_cvt_pk_bf16_f32 v52, v58, v59
	v_cvt_pk_bf16_f32 v53, v60, v61
	v_mul_f32_e32 v59, v59, v59
	v_mul_f32_e32 v61, v61, v61
	v_mul_f32_e32 v103, v101, v101
	v_fmac_f32_e32 v63, v62, v62
	v_fmac_f32_e32 v65, v64, v64
	v_fmac_f32_e32 v97, v54, v54
	v_fmac_f32_e32 v102, v56, v56
	v_mul_f32_e32 v104, v99, v99
	v_fmac_f32_e32 v59, v58, v58
	v_fmac_f32_e32 v61, v60, v60
	v_fmac_f32_e32 v103, v100, v100
	v_add_f32_e32 v58, v63, v65
	v_add_f32_e32 v60, v97, v102
	v_fmac_f32_e32 v104, v98, v98
	v_add_f32_e32 v58, v59, v58
	v_add_f32_e32 v59, v103, v60
	v_add_f32_e32 v58, v61, v58
	v_add_f32_e32 v59, v104, v59
	v_add_f32_e32 v60, v58, v59
	ds_bpermute_b32 v61, v179, v60
	v_lshl_add_u64 v[58:59], s[16:17], 0, v[106:107]
	v_lshl_add_u64 v[58:59], v[174:175], 1, v[58:59]
	global_store_dwordx4 v[58:59], v[50:53], off
	s_waitcnt lgkmcnt(0)
	s_nop 0
	v_add_f32_e32 v50, v60, v61
	ds_bpermute_b32 v51, v114, v50
	v_cvt_pk_bf16_f32 v52, v54, v55
	v_cvt_pk_bf16_f32 v53, v56, v57
	v_cvt_pk_bf16_f32 v54, v100, v101
	v_cvt_pk_bf16_f32 v55, v98, v99
	global_store_dwordx4 v[58:59], v[52:55], off offset:256
	s_and_saveexec_b64 s[40:41], s[4:5]
	s_cbranch_execz .LBB0_2353
	s_lshl_b32 s12, s3, 4
	s_add_i32 s44, s12, s33
	s_ashr_i32 s45, s44, 31
	s_lshl_b64 s[44:45], s[44:45], 12
	s_waitcnt lgkmcnt(0)
	v_add_f32_e32 v52, v50, v51
	v_subrev_u32_e32 v50, s42, v96
	s_add_u32 s44, s26, s44
	v_ashrrev_i32_e32 v51, 31, v50
	s_addc_u32 s45, s27, s45
	v_lshl_add_u64 v[50:51], v[50:51], 4, s[44:45]
	s_lshl_b32 s12, s50, 2
	v_lshl_add_u64 v[50:51], v[50:51], 0, s[12:13]
	global_store_dword v[50:51], v52, off
.LBB0_2353:
	s_or_b64 exec, exec, s[40:41]
	v_lshlrev_b32_e32 v52, 16, v220
	v_and_b32_e32 v53, 0xffff0000, v220
	v_lshlrev_b32_e32 v54, 16, v221
	v_and_b32_e32 v55, 0xffff0000, v221
	v_lshlrev_b32_e32 v56, 16, v222
	v_and_b32_e32 v57, 0xffff0000, v222
	v_pk_add_f32 v[46:47], v[46:47], v[52:53]
	v_pk_add_f32 v[48:49], v[48:49], v[54:55]
	v_pk_add_f32 v[54:55], v[42:43], v[56:57]
	v_cvt_pk_bf16_f32 v42, v46, v47
	v_mul_f32_e32 v47, v47, v47
	v_fmac_f32_e32 v47, v46, v46
	v_mul_f32_e32 v46, v49, v49
	v_fmac_f32_e32 v46, v48, v48
	v_lshlrev_b32_e32 v58, 16, v223
	v_and_b32_e32 v59, 0xffff0000, v223
	v_add_f32_e32 v46, v47, v46
	v_mul_f32_e32 v47, v55, v55
	v_pk_add_f32 v[52:53], v[44:45], v[58:59]
	v_fmac_f32_e32 v47, v54, v54
	v_add_f32_e32 v46, v47, v46
	v_mul_f32_e32 v47, v53, v53
	v_fmac_f32_e32 v47, v52, v52
	v_cvt_pk_bf16_f32 v43, v48, v49
	v_add_f32_e32 v56, v47, v46
	v_lshlrev_b32_e32 v46, 16, v224
	v_and_b32_e32 v47, 0xffff0000, v224
	v_lshlrev_b32_e32 v48, 16, v225
	v_and_b32_e32 v49, 0xffff0000, v225
	v_cvt_pk_bf16_f32 v44, v54, v55
	v_cvt_pk_bf16_f32 v45, v52, v53
	v_lshlrev_b32_e32 v52, 16, v226
	v_and_b32_e32 v53, 0xffff0000, v226
	v_pk_add_f32 v[40:41], v[40:41], v[48:49]
	v_pk_add_f32 v[38:39], v[38:39], v[46:47]
	v_pk_add_f32 v[48:49], v[34:35], v[52:53]
	v_mul_f32_e32 v34, v39, v39
	v_mul_f32_e32 v35, v41, v41
	v_fmac_f32_e32 v34, v38, v38
	v_fmac_f32_e32 v35, v40, v40
	v_lshlrev_b32_e32 v54, 16, v227
	v_and_b32_e32 v55, 0xffff0000, v227
	v_add_f32_e32 v34, v34, v35
	v_mul_f32_e32 v35, v49, v49
	v_pk_add_f32 v[46:47], v[36:37], v[54:55]
	v_fmac_f32_e32 v35, v48, v48
	v_add_f32_e32 v34, v35, v34
	v_mul_f32_e32 v35, v47, v47
	v_fmac_f32_e32 v35, v46, v46
	v_add_f32_e32 v34, v35, v34
	v_add_f32_e32 v37, v56, v34
	ds_bpermute_b32 v52, v179, v37
	s_waitcnt lgkmcnt(1)
	v_lshlrev_b64 v[50:51], 12, v[94:95]
	v_lshl_add_u64 v[34:35], v[50:51], 1, s[16:17]
	v_lshl_add_u64 v[50:51], v[174:175], 1, v[34:35]
	global_store_dwordx4 v[50:51], v[42:45], off
	s_waitcnt lgkmcnt(0)
	v_add_f32_e32 v34, v37, v52
	ds_bpermute_b32 v35, v114, v34
	v_cvt_pk_bf16_f32 v36, v38, v39
	v_cvt_pk_bf16_f32 v37, v40, v41
	v_cvt_pk_bf16_f32 v38, v48, v49
	v_cvt_pk_bf16_f32 v39, v46, v47
	global_store_dwordx4 v[50:51], v[36:39], off offset:256
	s_and_saveexec_b64 s[40:41], s[4:5]
	s_cbranch_execz .LBB0_2355
	s_lshl_b32 s12, s3, 4
	s_add_i32 s44, s12, s33
	s_ashr_i32 s45, s44, 31
	s_lshl_b64 s[44:45], s[44:45], 12
	s_waitcnt lgkmcnt(0)
	v_add_f32_e32 v36, v34, v35
	v_subrev_u32_e32 v34, s42, v94
	s_add_u32 s44, s26, s44
	v_ashrrev_i32_e32 v35, 31, v34
	s_addc_u32 s45, s27, s45
	v_lshl_add_u64 v[34:35], v[34:35], 4, s[44:45]
	s_lshl_b32 s12, s50, 2
	v_lshl_add_u64 v[34:35], v[34:35], 0, s[12:13]
	global_store_dword v[34:35], v36, off
.LBB0_2355:
	s_or_b64 exec, exec, s[40:41]
	v_lshlrev_b32_e32 v36, 16, v228
	v_and_b32_e32 v37, 0xffff0000, v228
	v_lshlrev_b32_e32 v38, 16, v229
	v_and_b32_e32 v39, 0xffff0000, v229
	v_lshlrev_b32_e32 v40, 16, v230
	v_and_b32_e32 v41, 0xffff0000, v230
	v_pk_add_f32 v[30:31], v[30:31], v[36:37]
	v_pk_add_f32 v[32:33], v[32:33], v[38:39]
	v_pk_add_f32 v[38:39], v[26:27], v[40:41]
	v_cvt_pk_bf16_f32 v26, v30, v31
	v_mul_f32_e32 v31, v31, v31
	v_fmac_f32_e32 v31, v30, v30
	v_mul_f32_e32 v30, v33, v33
	v_fmac_f32_e32 v30, v32, v32
	v_lshlrev_b32_e32 v42, 16, v231
	v_and_b32_e32 v43, 0xffff0000, v231
	v_add_f32_e32 v30, v31, v30
	v_mul_f32_e32 v31, v39, v39
	v_pk_add_f32 v[36:37], v[28:29], v[42:43]
	v_fmac_f32_e32 v31, v38, v38
	v_add_f32_e32 v30, v31, v30
	v_mul_f32_e32 v31, v37, v37
	v_fmac_f32_e32 v31, v36, v36
	v_cvt_pk_bf16_f32 v27, v32, v33
	v_add_f32_e32 v40, v31, v30
	v_lshlrev_b32_e32 v30, 16, v232
	v_and_b32_e32 v31, 0xffff0000, v232
	v_lshlrev_b32_e32 v32, 16, v233
	v_and_b32_e32 v33, 0xffff0000, v233
	v_cvt_pk_bf16_f32 v28, v38, v39
	v_cvt_pk_bf16_f32 v29, v36, v37
	v_lshlrev_b32_e32 v36, 16, v234
	v_and_b32_e32 v37, 0xffff0000, v234
	v_pk_add_f32 v[24:25], v[24:25], v[32:33]
	v_pk_add_f32 v[22:23], v[22:23], v[30:31]
	v_pk_add_f32 v[32:33], v[18:19], v[36:37]
	v_mul_f32_e32 v18, v23, v23
	v_mul_f32_e32 v19, v25, v25
	v_fmac_f32_e32 v18, v22, v22
	v_fmac_f32_e32 v19, v24, v24
	v_lshlrev_b32_e32 v38, 16, v235
	v_and_b32_e32 v39, 0xffff0000, v235
	v_add_f32_e32 v18, v18, v19
	v_mul_f32_e32 v19, v33, v33
	v_pk_add_f32 v[30:31], v[20:21], v[38:39]
	v_fmac_f32_e32 v19, v32, v32
	v_add_f32_e32 v18, v19, v18
	v_mul_f32_e32 v19, v31, v31
	v_fmac_f32_e32 v19, v30, v30
	v_add_f32_e32 v18, v19, v18
	v_add_f32_e32 v21, v40, v18
	ds_bpermute_b32 v36, v179, v21
	s_waitcnt lgkmcnt(1)
	v_lshlrev_b64 v[34:35], 12, v[92:93]
	v_lshl_add_u64 v[18:19], v[34:35], 1, s[16:17]
	v_lshl_add_u64 v[34:35], v[174:175], 1, v[18:19]
	global_store_dwordx4 v[34:35], v[26:29], off
	s_waitcnt lgkmcnt(0)
	v_add_f32_e32 v18, v21, v36
	ds_bpermute_b32 v19, v114, v18
	v_cvt_pk_bf16_f32 v20, v22, v23
	v_cvt_pk_bf16_f32 v21, v24, v25
	v_cvt_pk_bf16_f32 v22, v32, v33
	v_cvt_pk_bf16_f32 v23, v30, v31
	global_store_dwordx4 v[34:35], v[20:23], off offset:256
	s_and_saveexec_b64 s[40:41], s[4:5]
	s_cbranch_execz .LBB0_2357
	s_lshl_b32 s12, s3, 4
	s_add_i32 s44, s12, s33
	s_ashr_i32 s45, s44, 31
	s_lshl_b64 s[44:45], s[44:45], 12
	s_waitcnt lgkmcnt(0)
	v_add_f32_e32 v20, v18, v19
	v_subrev_u32_e32 v18, s42, v92
	s_add_u32 s44, s26, s44
	v_ashrrev_i32_e32 v19, 31, v18
	s_addc_u32 s45, s27, s45
	v_lshl_add_u64 v[18:19], v[18:19], 4, s[44:45]
	s_lshl_b32 s12, s50, 2
	v_lshl_add_u64 v[18:19], v[18:19], 0, s[12:13]
	global_store_dword v[18:19], v20, off
.LBB0_2357:
	s_or_b64 exec, exec, s[40:41]
	v_lshlrev_b32_e32 v20, 16, v236
	v_and_b32_e32 v21, 0xffff0000, v236
	v_lshlrev_b32_e32 v22, 16, v237
	v_and_b32_e32 v23, 0xffff0000, v237
	v_lshlrev_b32_e32 v24, 16, v238
	v_and_b32_e32 v25, 0xffff0000, v238
	v_pk_add_f32 v[14:15], v[14:15], v[20:21]
	v_pk_add_f32 v[16:17], v[16:17], v[22:23]
	v_pk_add_f32 v[22:23], v[10:11], v[24:25]
	v_cvt_pk_bf16_f32 v10, v14, v15
	v_mul_f32_e32 v15, v15, v15
	v_fmac_f32_e32 v15, v14, v14
	v_mul_f32_e32 v14, v17, v17
	v_fmac_f32_e32 v14, v16, v16
	v_lshlrev_b32_e32 v26, 16, v239
	v_and_b32_e32 v27, 0xffff0000, v239
	v_add_f32_e32 v14, v15, v14
	v_mul_f32_e32 v15, v23, v23
	v_pk_add_f32 v[20:21], v[12:13], v[26:27]
	v_fmac_f32_e32 v15, v22, v22
	v_add_f32_e32 v14, v15, v14
	v_mul_f32_e32 v15, v21, v21
	v_fmac_f32_e32 v15, v20, v20
	v_cvt_pk_bf16_f32 v11, v16, v17
	v_add_f32_e32 v24, v15, v14
	v_lshlrev_b32_e32 v14, 16, v240
	v_and_b32_e32 v15, 0xffff0000, v240
	v_lshlrev_b32_e32 v16, 16, v241
	v_and_b32_e32 v17, 0xffff0000, v241
	v_cvt_pk_bf16_f32 v12, v22, v23
	v_cvt_pk_bf16_f32 v13, v20, v21
	v_lshlrev_b32_e32 v20, 16, v242
	v_and_b32_e32 v21, 0xffff0000, v242
	v_pk_add_f32 v[8:9], v[8:9], v[16:17]
	v_pk_add_f32 v[6:7], v[6:7], v[14:15]
	v_pk_add_f32 v[16:17], v[2:3], v[20:21]
	v_mul_f32_e32 v2, v7, v7
	v_mul_f32_e32 v3, v9, v9
	v_fmac_f32_e32 v2, v6, v6
	v_fmac_f32_e32 v3, v8, v8
	v_lshlrev_b32_e32 v22, 16, v243
	v_and_b32_e32 v23, 0xffff0000, v243
	v_add_f32_e32 v2, v2, v3
	v_mul_f32_e32 v3, v17, v17
	v_pk_add_f32 v[14:15], v[4:5], v[22:23]
	v_fmac_f32_e32 v3, v16, v16
	v_add_f32_e32 v2, v3, v2
	v_mul_f32_e32 v3, v15, v15
	v_fmac_f32_e32 v3, v14, v14
	v_add_f32_e32 v2, v3, v2
	v_add_f32_e32 v5, v24, v2
	ds_bpermute_b32 v20, v179, v5
	s_waitcnt lgkmcnt(1)
	v_lshlrev_b64 v[18:19], 12, v[90:91]
	v_lshl_add_u64 v[2:3], v[18:19], 1, s[16:17]
	v_lshl_add_u64 v[18:19], v[174:175], 1, v[2:3]
	global_store_dwordx4 v[18:19], v[10:13], off
	s_waitcnt lgkmcnt(0)
	v_add_f32_e32 v2, v5, v20
	ds_bpermute_b32 v3, v114, v2
	v_cvt_pk_bf16_f32 v4, v6, v7
	v_cvt_pk_bf16_f32 v5, v8, v9
	v_cvt_pk_bf16_f32 v6, v16, v17
	v_cvt_pk_bf16_f32 v7, v14, v15
	global_store_dwordx4 v[18:19], v[4:7], off offset:256
	s_and_saveexec_b64 s[40:41], s[4:5]
	s_cbranch_execz .LBB0_2359
	s_lshl_b32 s3, s3, 4
	s_add_i32 s44, s3, s33
	s_ashr_i32 s45, s44, 31
	s_waitcnt lgkmcnt(0)
	v_add_f32_e32 v4, v2, v3
	v_subrev_u32_e32 v2, s42, v90
	s_lshl_b64 s[42:43], s[44:45], 12
	s_add_u32 s42, s26, s42
	v_ashrrev_i32_e32 v3, 31, v2
	s_addc_u32 s43, s27, s43
	v_lshl_add_u64 v[2:3], v[2:3], 4, s[42:43]
	s_lshl_b32 s12, s50, 2
	v_lshl_add_u64 v[2:3], v[2:3], 0, s[12:13]
	global_store_dword v[2:3], v4, off

.LBB0_2638:
	s_lshl_b32 s39, s12, 8
	v_lshl_or_b32 v174, s20, 8, v183
	v_add_u32_e32 v178, s39, v162
	v_ashrrev_i32_e32 v175, 31, v174
	v_lshlrev_b64 v[200:201], 1, v[174:175]
	v_ashrrev_i32_e32 v179, 31, v178
	v_lshl_add_u64 v[176:177], s[16:17], 0, v[200:201]
	v_lshlrev_b64 v[202:203], 13, v[178:179]
	v_lshl_add_u64 v[130:131], v[176:177], 0, v[202:203]
	global_load_dwordx4 v[192:195], v[130:131], off
	global_load_dwordx4 v[196:199], v[130:131], off offset:256
	v_or_b32_e32 v186, 16, v178
	v_or_b32_e32 v184, 32, v178
	v_or_b32_e32 v180, 48, v178
	v_ashrrev_i32_e32 v187, 31, v186
	v_ashrrev_i32_e32 v185, 31, v184
	v_ashrrev_i32_e32 v181, 31, v180
	v_lshlrev_b64 v[130:131], 13, v[186:187]
	v_lshlrev_b64 v[132:133], 13, v[184:185]
	v_lshlrev_b64 v[134:135], 13, v[180:181]
	v_lshl_add_u64 v[130:131], v[176:177], 0, v[130:131]
	v_lshl_add_u64 v[132:133], v[176:177], 0, v[132:133]
	v_lshl_add_u64 v[204:205], v[176:177], 0, v[134:135]
	global_load_dwordx4 v[150:153], v[130:131], off
	global_load_dwordx4 v[146:149], v[130:131], off offset:256
	global_load_dwordx4 v[142:145], v[132:133], off
	global_load_dwordx4 v[138:141], v[132:133], off offset:256
	global_load_dwordx4 v[134:137], v[204:205], off
	s_nop 0
	global_load_dwordx4 v[130:133], v[204:205], off offset:256
	v_add_u32_e32 v246, 0x80, v178
	v_ashrrev_i32_e32 v247, 31, v246
	v_lshlrev_b64 v[248:249], 13, v[246:247]
	v_lshl_add_u64 v[250:251], v[176:177], 0, v[248:249]
	global_load_dwordx4 v[212:215], v[250:251], off
	global_load_dwordx4 v[216:219], v[250:251], off offset:256
	v_add_u32_e32 v246, 0x90, v178
	v_ashrrev_i32_e32 v247, 31, v246
	v_lshlrev_b64 v[248:249], 13, v[246:247]
	v_lshl_add_u64 v[252:253], v[176:177], 0, v[248:249]
	global_load_dwordx4 v[220:223], v[252:253], off
	global_load_dwordx4 v[224:227], v[252:253], off offset:256
	v_add_u32_e32 v246, 0xa0, v178
	v_ashrrev_i32_e32 v247, 31, v246
	v_lshlrev_b64 v[248:249], 13, v[246:247]
	v_lshl_add_u64 v[254:255], v[176:177], 0, v[248:249]
	global_load_dwordx4 v[228:231], v[254:255], off
	global_load_dwordx4 v[232:235], v[254:255], off offset:256
	v_add_u32_e32 v246, 0xb0, v178
	v_ashrrev_i32_e32 v247, 31, v246
	v_lshlrev_b64 v[248:249], 13, v[246:247]
	v_lshl_add_u64 v[250:251], v[176:177], 0, v[248:249]
	global_load_dwordx4 v[236:239], v[250:251], off
	global_load_dwordx4 v[240:243], v[250:251], off offset:256
	v_and_b32_e32 v191, 64, v190
	v_xor_b32_e32 v179, 16, v190
	v_add_u32_e32 v191, 64, v191
	v_xor_b32_e32 v204, 32, v190
	v_cmp_lt_i32_e32 vcc, v179, v191
	v_lshl_add_u64 v[202:203], s[16:17], 0, v[202:203]
	v_lshl_add_u64 v[200:201], v[202:203], 0, v[200:201]
	v_cndmask_b32_e32 v179, v190, v179, vcc
	v_cmp_lt_i32_e32 vcc, v204, v191
	v_lshlrev_b32_e32 v179, 2, v179
	s_waitcnt vmcnt(8)
	v_lshlrev_b32_e32 v202, 16, v192
	v_and_b32_e32 v203, 0xffff0000, v192
	v_lshlrev_b32_e32 v192, 16, v193
	v_and_b32_e32 v193, 0xffff0000, v193
	v_lshlrev_b32_e32 v206, 16, v196
	v_and_b32_e32 v207, 0xffff0000, v196
	v_lshlrev_b32_e32 v196, 16, v197
	v_and_b32_e32 v197, 0xffff0000, v197
	v_cndmask_b32_e32 v191, v190, v204, vcc
	v_lshlrev_b32_e32 v204, 16, v194
	v_and_b32_e32 v205, 0xffff0000, v194
	v_lshlrev_b32_e32 v194, 16, v195
	v_and_b32_e32 v195, 0xffff0000, v195
	v_lshlrev_b32_e32 v208, 16, v198
	v_and_b32_e32 v209, 0xffff0000, v198
	v_lshlrev_b32_e32 v198, 16, v199
	v_and_b32_e32 v199, 0xffff0000, v199
	v_pk_add_f32 v[128:129], v[128:129], v[192:193]
	v_pk_add_f32 v[126:127], v[126:127], v[202:203]
	v_pk_add_f32 v[120:121], v[120:121], v[196:197]
	v_pk_add_f32 v[118:119], v[118:119], v[206:207]
	v_pk_add_f32 v[124:125], v[124:125], v[194:195]
	v_pk_add_f32 v[122:123], v[122:123], v[204:205]
	v_pk_add_f32 v[192:193], v[116:117], v[198:199]
	v_pk_add_f32 v[194:195], v[114:115], v[208:209]
	v_mul_f32_e32 v116, v127, v127
	v_mul_f32_e32 v117, v129, v129
	v_mul_f32_e32 v196, v119, v119
	v_mul_f32_e32 v197, v121, v121
	v_cvt_pk_bf16_f32 v114, v126, v127
	v_mul_f32_e32 v127, v123, v123
	v_mul_f32_e32 v198, v195, v195
	v_fmac_f32_e32 v116, v126, v126
	v_fmac_f32_e32 v117, v128, v128
	v_fmac_f32_e32 v196, v118, v118
	v_fmac_f32_e32 v197, v120, v120
	v_cvt_pk_bf16_f32 v115, v128, v129
	v_mul_f32_e32 v129, v125, v125
	v_mul_f32_e32 v199, v193, v193
	v_fmac_f32_e32 v127, v122, v122
	v_fmac_f32_e32 v198, v194, v194
	v_add_f32_e32 v116, v116, v117
	v_add_f32_e32 v117, v196, v197
	v_fmac_f32_e32 v129, v124, v124
	v_fmac_f32_e32 v199, v192, v192
	v_add_f32_e32 v116, v127, v116
	v_add_f32_e32 v117, v198, v117
	v_add_f32_e32 v116, v129, v116
	v_add_f32_e32 v117, v199, v117
	v_add_f32_e32 v126, v116, v117
	ds_bpermute_b32 v127, v179, v126
	v_cvt_pk_bf16_f32 v116, v122, v123
	v_cvt_pk_bf16_f32 v117, v124, v125
	global_store_dwordx4 v[200:201], v[114:117], off
	v_cvt_pk_bf16_f32 v118, v118, v119
	v_cvt_pk_bf16_f32 v119, v120, v121
	v_cvt_pk_bf16_f32 v120, v194, v195
	v_cvt_pk_bf16_f32 v121, v192, v193
	global_store_dwordx4 v[200:201], v[118:121], off offset:256
	s_waitcnt lgkmcnt(0)
	v_add_f32_e32 v115, v126, v127
	v_lshlrev_b32_e32 v114, 2, v191
	ds_bpermute_b32 v116, v114, v115
	s_and_saveexec_b64 s[46:47], s[4:5]
	s_cbranch_execz .LBB0_2640
	s_lshl_b32 s22, s12, 4
	s_add_i32 s48, s22, s20
	s_ashr_i32 s49, s48, 31
	s_lshl_b64 s[48:49], s[48:49], 12
	s_waitcnt lgkmcnt(0)
	v_add_f32_e32 v115, v115, v116
	v_lshl_add_u64 v[116:117], v[164:165], 0, s[48:49]
	global_store_dword v[116:117], v115, off

.LBB0_2646:
	s_or_b64 exec, exec, s[46:47]
	v_add_u32_e32 v96, 0x80, v178
	v_ashrrev_i32_e32 v97, 31, v96
	v_lshlrev_b64 v[106:107], 13, v[96:97]
	s_waitcnt lgkmcnt(0)
	v_lshl_add_u64 v[66:67], v[176:177], 0, v[106:107]
	v_add_u32_e32 v94, 0x90, v178
	v_add_u32_e32 v92, 0xa0, v178
	v_add_u32_e32 v90, 0xb0, v178
	v_ashrrev_i32_e32 v95, 31, v94
	v_ashrrev_i32_e32 v93, 31, v92
	v_ashrrev_i32_e32 v91, 31, v90
	v_lshlrev_b64 v[66:67], 13, v[94:95]
	v_lshlrev_b64 v[68:69], 13, v[92:93]
	v_lshlrev_b64 v[70:71], 13, v[90:91]
	v_lshl_add_u64 v[66:67], v[176:177], 0, v[66:67]
	v_lshl_add_u64 v[68:69], v[176:177], 0, v[68:69]
	v_lshl_add_u64 v[108:109], v[176:177], 0, v[70:71]
	s_waitcnt vmcnt(8)
	v_lshlrev_b32_e32 v108, 16, v212
	v_and_b32_e32 v109, 0xffff0000, v212
	v_lshlrev_b32_e32 v98, 16, v213
	v_and_b32_e32 v99, 0xffff0000, v213
	v_lshlrev_b32_e32 v112, 16, v216
	v_and_b32_e32 v113, 0xffff0000, v216
	v_lshlrev_b32_e32 v102, 16, v217
	v_and_b32_e32 v103, 0xffff0000, v217
	v_lshlrev_b32_e32 v110, 16, v214
	v_and_b32_e32 v111, 0xffff0000, v214
	v_lshlrev_b32_e32 v100, 16, v215
	v_and_b32_e32 v101, 0xffff0000, v215
	v_lshlrev_b32_e32 v116, 16, v218
	v_and_b32_e32 v117, 0xffff0000, v218
	v_pk_add_f32 v[64:65], v[64:65], v[98:99]
	v_pk_add_f32 v[62:63], v[62:63], v[108:109]
	v_pk_add_f32 v[56:57], v[56:57], v[102:103]
	v_pk_add_f32 v[54:55], v[54:55], v[112:113]
	v_lshlrev_b32_e32 v104, 16, v219
	v_and_b32_e32 v105, 0xffff0000, v219
	v_pk_add_f32 v[60:61], v[60:61], v[100:101]
	v_pk_add_f32 v[58:59], v[58:59], v[110:111]
	v_pk_add_f32 v[100:101], v[50:51], v[116:117]
	v_cvt_pk_bf16_f32 v50, v62, v63
	v_cvt_pk_bf16_f32 v51, v64, v65
	v_mul_f32_e32 v63, v63, v63
	v_mul_f32_e32 v65, v65, v65
	v_mul_f32_e32 v97, v55, v55
	v_mul_f32_e32 v102, v57, v57
	v_pk_add_f32 v[98:99], v[52:53], v[104:105]
	v_cvt_pk_bf16_f32 v52, v58, v59
	v_cvt_pk_bf16_f32 v53, v60, v61
	v_mul_f32_e32 v59, v59, v59
	v_mul_f32_e32 v61, v61, v61
	v_mul_f32_e32 v103, v101, v101
	v_fmac_f32_e32 v63, v62, v62
	v_fmac_f32_e32 v65, v64, v64
	v_fmac_f32_e32 v97, v54, v54
	v_fmac_f32_e32 v102, v56, v56
	v_mul_f32_e32 v104, v99, v99
	v_fmac_f32_e32 v59, v58, v58
	v_fmac_f32_e32 v61, v60, v60
	v_fmac_f32_e32 v103, v100, v100
	v_add_f32_e32 v58, v63, v65
	v_add_f32_e32 v60, v97, v102
	v_fmac_f32_e32 v104, v98, v98
	v_add_f32_e32 v58, v59, v58
	v_add_f32_e32 v59, v103, v60
	v_add_f32_e32 v58, v61, v58
	v_add_f32_e32 v59, v104, v59
	v_add_f32_e32 v60, v58, v59
	ds_bpermute_b32 v61, v179, v60
	v_lshl_add_u64 v[58:59], s[16:17], 0, v[106:107]
	v_lshl_add_u64 v[58:59], v[174:175], 1, v[58:59]
	global_store_dwordx4 v[58:59], v[50:53], off
	s_waitcnt lgkmcnt(0)
	s_nop 0
	v_add_f32_e32 v50, v60, v61
	ds_bpermute_b32 v51, v114, v50
	v_cvt_pk_bf16_f32 v52, v54, v55
	v_cvt_pk_bf16_f32 v53, v56, v57
	v_cvt_pk_bf16_f32 v54, v100, v101
	v_cvt_pk_bf16_f32 v55, v98, v99
	global_store_dwordx4 v[58:59], v[52:55], off offset:256
	s_and_saveexec_b64 s[46:47], s[4:5]
	s_cbranch_execz .LBB0_2648
	s_lshl_b32 s22, s12, 4
	s_add_i32 s48, s22, s20
	s_ashr_i32 s49, s48, 31
	s_lshl_b64 s[48:49], s[48:49], 12
	s_waitcnt lgkmcnt(0)
	v_add_f32_e32 v52, v50, v51
	v_subrev_u32_e32 v50, s39, v96
	s_add_u32 s48, s26, s48
	v_ashrrev_i32_e32 v51, 31, v50
	s_addc_u32 s49, s27, s49
	v_lshl_add_u64 v[50:51], v[50:51], 4, s[48:49]
	s_lshl_b32 s22, s59, 2
	v_lshl_add_u64 v[50:51], v[50:51], 0, s[22:23]
	global_store_dword v[50:51], v52, off
.LBB0_2648:
	s_or_b64 exec, exec, s[46:47]
	v_lshlrev_b32_e32 v52, 16, v220
	v_and_b32_e32 v53, 0xffff0000, v220
	v_lshlrev_b32_e32 v54, 16, v221
	v_and_b32_e32 v55, 0xffff0000, v221
	v_lshlrev_b32_e32 v56, 16, v222
	v_and_b32_e32 v57, 0xffff0000, v222
	v_pk_add_f32 v[46:47], v[46:47], v[52:53]
	v_pk_add_f32 v[48:49], v[48:49], v[54:55]
	v_pk_add_f32 v[54:55], v[42:43], v[56:57]
	v_cvt_pk_bf16_f32 v42, v46, v47
	v_mul_f32_e32 v47, v47, v47
	v_fmac_f32_e32 v47, v46, v46
	v_mul_f32_e32 v46, v49, v49
	v_fmac_f32_e32 v46, v48, v48
	v_lshlrev_b32_e32 v58, 16, v223
	v_and_b32_e32 v59, 0xffff0000, v223
	v_add_f32_e32 v46, v47, v46
	v_mul_f32_e32 v47, v55, v55
	v_pk_add_f32 v[52:53], v[44:45], v[58:59]
	v_fmac_f32_e32 v47, v54, v54
	v_add_f32_e32 v46, v47, v46
	v_mul_f32_e32 v47, v53, v53
	v_fmac_f32_e32 v47, v52, v52
	v_cvt_pk_bf16_f32 v43, v48, v49
	v_add_f32_e32 v56, v47, v46
	v_lshlrev_b32_e32 v46, 16, v224
	v_and_b32_e32 v47, 0xffff0000, v224
	v_lshlrev_b32_e32 v48, 16, v225
	v_and_b32_e32 v49, 0xffff0000, v225
	v_cvt_pk_bf16_f32 v44, v54, v55
	v_cvt_pk_bf16_f32 v45, v52, v53
	v_lshlrev_b32_e32 v52, 16, v226
	v_and_b32_e32 v53, 0xffff0000, v226
	v_pk_add_f32 v[40:41], v[40:41], v[48:49]
	v_pk_add_f32 v[38:39], v[38:39], v[46:47]
	v_pk_add_f32 v[48:49], v[34:35], v[52:53]
	v_mul_f32_e32 v34, v39, v39
	v_mul_f32_e32 v35, v41, v41
	v_fmac_f32_e32 v34, v38, v38
	v_fmac_f32_e32 v35, v40, v40
	v_lshlrev_b32_e32 v54, 16, v227
	v_and_b32_e32 v55, 0xffff0000, v227
	v_add_f32_e32 v34, v34, v35
	v_mul_f32_e32 v35, v49, v49
	v_pk_add_f32 v[46:47], v[36:37], v[54:55]
	v_fmac_f32_e32 v35, v48, v48
	v_add_f32_e32 v34, v35, v34
	v_mul_f32_e32 v35, v47, v47
	v_fmac_f32_e32 v35, v46, v46
	v_add_f32_e32 v34, v35, v34
	v_add_f32_e32 v37, v56, v34
	ds_bpermute_b32 v52, v179, v37
	s_waitcnt lgkmcnt(1)
	v_lshlrev_b64 v[50:51], 12, v[94:95]
	v_lshl_add_u64 v[34:35], v[50:51], 1, s[16:17]
	v_lshl_add_u64 v[50:51], v[174:175], 1, v[34:35]
	global_store_dwordx4 v[50:51], v[42:45], off
	s_waitcnt lgkmcnt(0)
	v_add_f32_e32 v34, v37, v52
	ds_bpermute_b32 v35, v114, v34
	v_cvt_pk_bf16_f32 v36, v38, v39
	v_cvt_pk_bf16_f32 v37, v40, v41
	v_cvt_pk_bf16_f32 v38, v48, v49
	v_cvt_pk_bf16_f32 v39, v46, v47
	global_store_dwordx4 v[50:51], v[36:39], off offset:256
	s_and_saveexec_b64 s[46:47], s[4:5]
	s_cbranch_execz .LBB0_2650
	s_lshl_b32 s22, s12, 4
	s_add_i32 s48, s22, s20
	s_ashr_i32 s49, s48, 31
	s_lshl_b64 s[48:49], s[48:49], 12
	s_waitcnt lgkmcnt(0)
	v_add_f32_e32 v36, v34, v35
	v_subrev_u32_e32 v34, s39, v94
	s_add_u32 s48, s26, s48
	v_ashrrev_i32_e32 v35, 31, v34
	s_addc_u32 s49, s27, s49
	v_lshl_add_u64 v[34:35], v[34:35], 4, s[48:49]
	s_lshl_b32 s22, s59, 2
	v_lshl_add_u64 v[34:35], v[34:35], 0, s[22:23]
	global_store_dword v[34:35], v36, off
.LBB0_2650:
	s_or_b64 exec, exec, s[46:47]
	v_lshlrev_b32_e32 v36, 16, v228
	v_and_b32_e32 v37, 0xffff0000, v228
	v_lshlrev_b32_e32 v38, 16, v229
	v_and_b32_e32 v39, 0xffff0000, v229
	v_lshlrev_b32_e32 v40, 16, v230
	v_and_b32_e32 v41, 0xffff0000, v230
	v_pk_add_f32 v[30:31], v[30:31], v[36:37]
	v_pk_add_f32 v[32:33], v[32:33], v[38:39]
	v_pk_add_f32 v[38:39], v[26:27], v[40:41]
	v_cvt_pk_bf16_f32 v26, v30, v31
	v_mul_f32_e32 v31, v31, v31
	v_fmac_f32_e32 v31, v30, v30
	v_mul_f32_e32 v30, v33, v33
	v_fmac_f32_e32 v30, v32, v32
	v_lshlrev_b32_e32 v42, 16, v231
	v_and_b32_e32 v43, 0xffff0000, v231
	v_add_f32_e32 v30, v31, v30
	v_mul_f32_e32 v31, v39, v39
	v_pk_add_f32 v[36:37], v[28:29], v[42:43]
	v_fmac_f32_e32 v31, v38, v38
	v_add_f32_e32 v30, v31, v30
	v_mul_f32_e32 v31, v37, v37
	v_fmac_f32_e32 v31, v36, v36
	v_cvt_pk_bf16_f32 v27, v32, v33
	v_add_f32_e32 v40, v31, v30
	v_lshlrev_b32_e32 v30, 16, v232
	v_and_b32_e32 v31, 0xffff0000, v232
	v_lshlrev_b32_e32 v32, 16, v233
	v_and_b32_e32 v33, 0xffff0000, v233
	v_cvt_pk_bf16_f32 v28, v38, v39
	v_cvt_pk_bf16_f32 v29, v36, v37
	v_lshlrev_b32_e32 v36, 16, v234
	v_and_b32_e32 v37, 0xffff0000, v234
	v_pk_add_f32 v[24:25], v[24:25], v[32:33]
	v_pk_add_f32 v[22:23], v[22:23], v[30:31]
	v_pk_add_f32 v[32:33], v[18:19], v[36:37]
	v_mul_f32_e32 v18, v23, v23
	v_mul_f32_e32 v19, v25, v25
	v_fmac_f32_e32 v18, v22, v22
	v_fmac_f32_e32 v19, v24, v24
	v_lshlrev_b32_e32 v38, 16, v235
	v_and_b32_e32 v39, 0xffff0000, v235
	v_add_f32_e32 v18, v18, v19
	v_mul_f32_e32 v19, v33, v33
	v_pk_add_f32 v[30:31], v[20:21], v[38:39]
	v_fmac_f32_e32 v19, v32, v32
	v_add_f32_e32 v18, v19, v18
	v_mul_f32_e32 v19, v31, v31
	v_fmac_f32_e32 v19, v30, v30
	v_add_f32_e32 v18, v19, v18
	v_add_f32_e32 v21, v40, v18
	ds_bpermute_b32 v36, v179, v21
	s_waitcnt lgkmcnt(1)
	v_lshlrev_b64 v[34:35], 12, v[92:93]
	v_lshl_add_u64 v[18:19], v[34:35], 1, s[16:17]
	v_lshl_add_u64 v[34:35], v[174:175], 1, v[18:19]
	global_store_dwordx4 v[34:35], v[26:29], off
	s_waitcnt lgkmcnt(0)
	v_add_f32_e32 v18, v21, v36
	ds_bpermute_b32 v19, v114, v18
	v_cvt_pk_bf16_f32 v20, v22, v23
	v_cvt_pk_bf16_f32 v21, v24, v25
	v_cvt_pk_bf16_f32 v22, v32, v33
	v_cvt_pk_bf16_f32 v23, v30, v31
	global_store_dwordx4 v[34:35], v[20:23], off offset:256
	s_and_saveexec_b64 s[46:47], s[4:5]
	s_cbranch_execz .LBB0_2652
	s_lshl_b32 s22, s12, 4
	s_add_i32 s48, s22, s20
	s_ashr_i32 s49, s48, 31
	s_lshl_b64 s[48:49], s[48:49], 12
	s_waitcnt lgkmcnt(0)
	v_add_f32_e32 v20, v18, v19
	v_subrev_u32_e32 v18, s39, v92
	s_add_u32 s48, s26, s48
	v_ashrrev_i32_e32 v19, 31, v18
	s_addc_u32 s49, s27, s49
	v_lshl_add_u64 v[18:19], v[18:19], 4, s[48:49]
	s_lshl_b32 s22, s59, 2
	v_lshl_add_u64 v[18:19], v[18:19], 0, s[22:23]
	global_store_dword v[18:19], v20, off
.LBB0_2652:
	s_or_b64 exec, exec, s[46:47]
	v_lshlrev_b32_e32 v20, 16, v236
	v_and_b32_e32 v21, 0xffff0000, v236
	v_lshlrev_b32_e32 v22, 16, v237
	v_and_b32_e32 v23, 0xffff0000, v237
	v_lshlrev_b32_e32 v24, 16, v238
	v_and_b32_e32 v25, 0xffff0000, v238
	v_pk_add_f32 v[14:15], v[14:15], v[20:21]
	v_pk_add_f32 v[16:17], v[16:17], v[22:23]
	v_pk_add_f32 v[22:23], v[10:11], v[24:25]
	v_cvt_pk_bf16_f32 v10, v14, v15
	v_mul_f32_e32 v15, v15, v15
	v_fmac_f32_e32 v15, v14, v14
	v_mul_f32_e32 v14, v17, v17
	v_fmac_f32_e32 v14, v16, v16
	v_lshlrev_b32_e32 v26, 16, v239
	v_and_b32_e32 v27, 0xffff0000, v239
	v_add_f32_e32 v14, v15, v14
	v_mul_f32_e32 v15, v23, v23
	v_pk_add_f32 v[20:21], v[12:13], v[26:27]
	v_fmac_f32_e32 v15, v22, v22
	v_add_f32_e32 v14, v15, v14
	v_mul_f32_e32 v15, v21, v21
	v_fmac_f32_e32 v15, v20, v20
	v_cvt_pk_bf16_f32 v11, v16, v17
	v_add_f32_e32 v24, v15, v14
	v_lshlrev_b32_e32 v14, 16, v240
	v_and_b32_e32 v15, 0xffff0000, v240
	v_lshlrev_b32_e32 v16, 16, v241
	v_and_b32_e32 v17, 0xffff0000, v241
	v_cvt_pk_bf16_f32 v12, v22, v23
	v_cvt_pk_bf16_f32 v13, v20, v21
	v_lshlrev_b32_e32 v20, 16, v242
	v_and_b32_e32 v21, 0xffff0000, v242
	v_pk_add_f32 v[8:9], v[8:9], v[16:17]
	v_pk_add_f32 v[6:7], v[6:7], v[14:15]
	v_pk_add_f32 v[16:17], v[2:3], v[20:21]
	v_mul_f32_e32 v2, v7, v7
	v_mul_f32_e32 v3, v9, v9
	v_fmac_f32_e32 v2, v6, v6
	v_fmac_f32_e32 v3, v8, v8
	v_lshlrev_b32_e32 v22, 16, v243
	v_and_b32_e32 v23, 0xffff0000, v243
	v_add_f32_e32 v2, v2, v3
	v_mul_f32_e32 v3, v17, v17
	v_pk_add_f32 v[14:15], v[4:5], v[22:23]
	v_fmac_f32_e32 v3, v16, v16
	v_add_f32_e32 v2, v3, v2
	v_mul_f32_e32 v3, v15, v15
	v_fmac_f32_e32 v3, v14, v14
	v_add_f32_e32 v2, v3, v2
	v_add_f32_e32 v5, v24, v2
	ds_bpermute_b32 v20, v179, v5
	s_waitcnt lgkmcnt(1)
	v_lshlrev_b64 v[18:19], 12, v[90:91]
	v_lshl_add_u64 v[2:3], v[18:19], 1, s[16:17]
	v_lshl_add_u64 v[18:19], v[174:175], 1, v[2:3]
	global_store_dwordx4 v[18:19], v[10:13], off
	s_waitcnt lgkmcnt(0)
	v_add_f32_e32 v2, v5, v20
	ds_bpermute_b32 v3, v114, v2
	v_cvt_pk_bf16_f32 v4, v6, v7
	v_cvt_pk_bf16_f32 v5, v8, v9
	v_cvt_pk_bf16_f32 v6, v16, v17
	v_cvt_pk_bf16_f32 v7, v14, v15
	global_store_dwordx4 v[18:19], v[4:7], off offset:256
	s_and_saveexec_b64 s[46:47], s[4:5]
	s_cbranch_execz .LBB0_2654
	s_lshl_b32 s12, s12, 4
	s_add_i32 s48, s12, s20
	s_ashr_i32 s49, s48, 31
	s_lshl_b64 s[48:49], s[48:49], 12
	s_waitcnt lgkmcnt(0)
	v_add_f32_e32 v4, v2, v3
	v_subrev_u32_e32 v2, s39, v90
	s_add_u32 s48, s26, s48
	v_ashrrev_i32_e32 v3, 31, v2
	s_addc_u32 s49, s27, s49
	v_lshl_add_u64 v[2:3], v[2:3], 4, s[48:49]
	s_lshl_b32 s22, s59, 2
	v_lshl_add_u64 v[2:3], v[2:3], 0, s[22:23]
	global_store_dword v[2:3], v4, off

.LBB0_2808:
	s_lshl_b32 s28, s3, 8
	v_lshl_or_b32 v174, s33, 8, v183
	v_add_u32_e32 v178, s28, v162
	v_ashrrev_i32_e32 v175, 31, v174
	v_lshlrev_b64 v[200:201], 1, v[174:175]
	v_ashrrev_i32_e32 v179, 31, v178
	v_lshl_add_u64 v[176:177], s[16:17], 0, v[200:201]
	v_lshlrev_b64 v[202:203], 13, v[178:179]
	v_lshl_add_u64 v[130:131], v[176:177], 0, v[202:203]
	global_load_dwordx4 v[192:195], v[130:131], off
	global_load_dwordx4 v[196:199], v[130:131], off offset:256
	v_or_b32_e32 v186, 16, v178
	v_or_b32_e32 v184, 32, v178
	v_or_b32_e32 v180, 48, v178
	v_ashrrev_i32_e32 v187, 31, v186
	v_ashrrev_i32_e32 v185, 31, v184
	v_ashrrev_i32_e32 v181, 31, v180
	v_lshlrev_b64 v[130:131], 13, v[186:187]
	v_lshlrev_b64 v[132:133], 13, v[184:185]
	v_lshlrev_b64 v[134:135], 13, v[180:181]
	v_lshl_add_u64 v[130:131], v[176:177], 0, v[130:131]
	v_lshl_add_u64 v[132:133], v[176:177], 0, v[132:133]
	v_lshl_add_u64 v[204:205], v[176:177], 0, v[134:135]
	global_load_dwordx4 v[150:153], v[130:131], off
	global_load_dwordx4 v[146:149], v[130:131], off offset:256
	global_load_dwordx4 v[142:145], v[132:133], off
	global_load_dwordx4 v[138:141], v[132:133], off offset:256
	global_load_dwordx4 v[134:137], v[204:205], off
	s_nop 0
	global_load_dwordx4 v[130:133], v[204:205], off offset:256
	v_add_u32_e32 v246, 0x80, v178
	v_ashrrev_i32_e32 v247, 31, v246
	v_lshlrev_b64 v[248:249], 13, v[246:247]
	v_lshl_add_u64 v[250:251], v[176:177], 0, v[248:249]
	global_load_dwordx4 v[212:215], v[250:251], off
	global_load_dwordx4 v[216:219], v[250:251], off offset:256
	v_add_u32_e32 v246, 0x90, v178
	v_ashrrev_i32_e32 v247, 31, v246
	v_lshlrev_b64 v[248:249], 13, v[246:247]
	v_lshl_add_u64 v[252:253], v[176:177], 0, v[248:249]
	global_load_dwordx4 v[220:223], v[252:253], off
	global_load_dwordx4 v[224:227], v[252:253], off offset:256
	v_add_u32_e32 v246, 0xa0, v178
	v_ashrrev_i32_e32 v247, 31, v246
	v_lshlrev_b64 v[248:249], 13, v[246:247]
	v_lshl_add_u64 v[254:255], v[176:177], 0, v[248:249]
	global_load_dwordx4 v[228:231], v[254:255], off
	global_load_dwordx4 v[232:235], v[254:255], off offset:256
	v_add_u32_e32 v246, 0xb0, v178
	v_ashrrev_i32_e32 v247, 31, v246
	v_lshlrev_b64 v[248:249], 13, v[246:247]
	v_lshl_add_u64 v[250:251], v[176:177], 0, v[248:249]
	global_load_dwordx4 v[236:239], v[250:251], off
	global_load_dwordx4 v[240:243], v[250:251], off offset:256
	v_and_b32_e32 v191, 64, v190
	v_xor_b32_e32 v179, 16, v190
	v_add_u32_e32 v191, 64, v191
	v_xor_b32_e32 v204, 32, v190
	v_cmp_lt_i32_e32 vcc, v179, v191
	v_lshl_add_u64 v[202:203], s[16:17], 0, v[202:203]
	v_lshl_add_u64 v[200:201], v[202:203], 0, v[200:201]
	v_cndmask_b32_e32 v179, v190, v179, vcc
	v_cmp_lt_i32_e32 vcc, v204, v191
	v_lshlrev_b32_e32 v179, 2, v179
	s_waitcnt vmcnt(8)
	v_lshlrev_b32_e32 v202, 16, v192
	v_and_b32_e32 v203, 0xffff0000, v192
	v_lshlrev_b32_e32 v192, 16, v193
	v_and_b32_e32 v193, 0xffff0000, v193
	v_lshlrev_b32_e32 v206, 16, v196
	v_and_b32_e32 v207, 0xffff0000, v196
	v_lshlrev_b32_e32 v196, 16, v197
	v_and_b32_e32 v197, 0xffff0000, v197
	v_cndmask_b32_e32 v191, v190, v204, vcc
	v_lshlrev_b32_e32 v204, 16, v194
	v_and_b32_e32 v205, 0xffff0000, v194
	v_lshlrev_b32_e32 v194, 16, v195
	v_and_b32_e32 v195, 0xffff0000, v195
	v_lshlrev_b32_e32 v208, 16, v198
	v_and_b32_e32 v209, 0xffff0000, v198
	v_lshlrev_b32_e32 v198, 16, v199
	v_and_b32_e32 v199, 0xffff0000, v199
	v_pk_add_f32 v[128:129], v[128:129], v[192:193]
	v_pk_add_f32 v[126:127], v[126:127], v[202:203]
	v_pk_add_f32 v[120:121], v[120:121], v[196:197]
	v_pk_add_f32 v[118:119], v[118:119], v[206:207]
	v_pk_add_f32 v[124:125], v[124:125], v[194:195]
	v_pk_add_f32 v[122:123], v[122:123], v[204:205]
	v_pk_add_f32 v[192:193], v[116:117], v[198:199]
	v_pk_add_f32 v[194:195], v[114:115], v[208:209]
	v_mul_f32_e32 v116, v127, v127
	v_mul_f32_e32 v117, v129, v129
	v_mul_f32_e32 v196, v119, v119
	v_mul_f32_e32 v197, v121, v121
	v_cvt_pk_bf16_f32 v114, v126, v127
	v_mul_f32_e32 v127, v123, v123
	v_mul_f32_e32 v198, v195, v195
	v_fmac_f32_e32 v116, v126, v126
	v_fmac_f32_e32 v117, v128, v128
	v_fmac_f32_e32 v196, v118, v118
	v_fmac_f32_e32 v197, v120, v120
	v_cvt_pk_bf16_f32 v115, v128, v129
	v_mul_f32_e32 v129, v125, v125
	v_mul_f32_e32 v199, v193, v193
	v_fmac_f32_e32 v127, v122, v122
	v_fmac_f32_e32 v198, v194, v194
	v_add_f32_e32 v116, v116, v117
	v_add_f32_e32 v117, v196, v197
	v_fmac_f32_e32 v129, v124, v124
	v_fmac_f32_e32 v199, v192, v192
	v_add_f32_e32 v116, v127, v116
	v_add_f32_e32 v117, v198, v117
	v_add_f32_e32 v116, v129, v116
	v_add_f32_e32 v117, v199, v117
	v_add_f32_e32 v126, v116, v117
	ds_bpermute_b32 v127, v179, v126
	v_cvt_pk_bf16_f32 v116, v122, v123
	v_cvt_pk_bf16_f32 v117, v124, v125
	global_store_dwordx4 v[200:201], v[114:117], off
	v_cvt_pk_bf16_f32 v118, v118, v119
	v_cvt_pk_bf16_f32 v119, v120, v121
	v_cvt_pk_bf16_f32 v120, v194, v195
	v_cvt_pk_bf16_f32 v121, v192, v193
	global_store_dwordx4 v[200:201], v[118:121], off offset:256
	s_waitcnt lgkmcnt(0)
	v_add_f32_e32 v115, v126, v127
	v_lshlrev_b32_e32 v114, 2, v191
	ds_bpermute_b32 v116, v114, v115
	s_and_saveexec_b64 s[26:27], s[0:1]
	s_cbranch_execz .LBB0_2810
	s_lshl_b32 s12, s3, 4
	s_add_i32 s36, s12, s33
	s_ashr_i32 s37, s36, 31
	s_lshl_b64 s[36:37], s[36:37], 12
	s_waitcnt lgkmcnt(0)
	v_add_f32_e32 v115, v115, v116
	v_lshl_add_u64 v[116:117], v[164:165], 0, s[36:37]
	global_store_dword v[116:117], v115, off

.LBB0_2816:
	s_or_b64 exec, exec, s[26:27]
	v_add_u32_e32 v96, 0x80, v178
	v_ashrrev_i32_e32 v97, 31, v96
	v_lshlrev_b64 v[106:107], 13, v[96:97]
	s_waitcnt lgkmcnt(0)
	v_lshl_add_u64 v[66:67], v[176:177], 0, v[106:107]
	v_add_u32_e32 v94, 0x90, v178
	v_add_u32_e32 v92, 0xa0, v178
	v_add_u32_e32 v90, 0xb0, v178
	v_ashrrev_i32_e32 v95, 31, v94
	v_ashrrev_i32_e32 v93, 31, v92
	v_ashrrev_i32_e32 v91, 31, v90
	v_lshlrev_b64 v[66:67], 13, v[94:95]
	v_lshlrev_b64 v[68:69], 13, v[92:93]
	v_lshlrev_b64 v[70:71], 13, v[90:91]
	v_lshl_add_u64 v[66:67], v[176:177], 0, v[66:67]
	v_lshl_add_u64 v[68:69], v[176:177], 0, v[68:69]
	v_lshl_add_u64 v[108:109], v[176:177], 0, v[70:71]
	s_waitcnt vmcnt(8)
	v_lshlrev_b32_e32 v108, 16, v212
	v_and_b32_e32 v109, 0xffff0000, v212
	v_lshlrev_b32_e32 v98, 16, v213
	v_and_b32_e32 v99, 0xffff0000, v213
	v_lshlrev_b32_e32 v112, 16, v216
	v_and_b32_e32 v113, 0xffff0000, v216
	v_lshlrev_b32_e32 v102, 16, v217
	v_and_b32_e32 v103, 0xffff0000, v217
	v_lshlrev_b32_e32 v110, 16, v214
	v_and_b32_e32 v111, 0xffff0000, v214
	v_lshlrev_b32_e32 v100, 16, v215
	v_and_b32_e32 v101, 0xffff0000, v215
	v_lshlrev_b32_e32 v116, 16, v218
	v_and_b32_e32 v117, 0xffff0000, v218
	v_pk_add_f32 v[64:65], v[64:65], v[98:99]
	v_pk_add_f32 v[62:63], v[62:63], v[108:109]
	v_pk_add_f32 v[56:57], v[56:57], v[102:103]
	v_pk_add_f32 v[54:55], v[54:55], v[112:113]
	v_lshlrev_b32_e32 v104, 16, v219
	v_and_b32_e32 v105, 0xffff0000, v219
	v_pk_add_f32 v[60:61], v[60:61], v[100:101]
	v_pk_add_f32 v[58:59], v[58:59], v[110:111]
	v_pk_add_f32 v[100:101], v[50:51], v[116:117]
	v_cvt_pk_bf16_f32 v50, v62, v63
	v_cvt_pk_bf16_f32 v51, v64, v65
	v_mul_f32_e32 v63, v63, v63
	v_mul_f32_e32 v65, v65, v65
	v_mul_f32_e32 v97, v55, v55
	v_mul_f32_e32 v102, v57, v57
	v_pk_add_f32 v[98:99], v[52:53], v[104:105]
	v_cvt_pk_bf16_f32 v52, v58, v59
	v_cvt_pk_bf16_f32 v53, v60, v61
	v_mul_f32_e32 v59, v59, v59
	v_mul_f32_e32 v61, v61, v61
	v_mul_f32_e32 v103, v101, v101
	v_fmac_f32_e32 v63, v62, v62
	v_fmac_f32_e32 v65, v64, v64
	v_fmac_f32_e32 v97, v54, v54
	v_fmac_f32_e32 v102, v56, v56
	v_mul_f32_e32 v104, v99, v99
	v_fmac_f32_e32 v59, v58, v58
	v_fmac_f32_e32 v61, v60, v60
	v_fmac_f32_e32 v103, v100, v100
	v_add_f32_e32 v58, v63, v65
	v_add_f32_e32 v60, v97, v102
	v_fmac_f32_e32 v104, v98, v98
	v_add_f32_e32 v58, v59, v58
	v_add_f32_e32 v59, v103, v60
	v_add_f32_e32 v58, v61, v58
	v_add_f32_e32 v59, v104, v59
	v_add_f32_e32 v60, v58, v59
	ds_bpermute_b32 v61, v179, v60
	v_lshl_add_u64 v[58:59], s[16:17], 0, v[106:107]
	v_lshl_add_u64 v[58:59], v[174:175], 1, v[58:59]
	global_store_dwordx4 v[58:59], v[50:53], off
	s_waitcnt lgkmcnt(0)
	s_nop 0
	v_add_f32_e32 v50, v60, v61
	ds_bpermute_b32 v51, v114, v50
	v_cvt_pk_bf16_f32 v52, v54, v55
	v_cvt_pk_bf16_f32 v53, v56, v57
	v_cvt_pk_bf16_f32 v54, v100, v101
	v_cvt_pk_bf16_f32 v55, v98, v99
	global_store_dwordx4 v[58:59], v[52:55], off offset:256
	s_and_saveexec_b64 s[26:27], s[0:1]
	s_cbranch_execz .LBB0_2818
	s_lshl_b32 s12, s3, 4
	s_add_i32 s36, s12, s33
	s_ashr_i32 s37, s36, 31
	s_lshl_b64 s[36:37], s[36:37], 12
	s_waitcnt lgkmcnt(0)
	v_add_f32_e32 v52, v50, v51
	v_subrev_u32_e32 v50, s28, v96
	s_add_u32 s36, s8, s36
	v_ashrrev_i32_e32 v51, 31, v50
	s_addc_u32 s37, s9, s37
	v_lshl_add_u64 v[50:51], v[50:51], 4, s[36:37]
	s_lshl_b32 s12, s42, 2
	v_lshl_add_u64 v[50:51], v[50:51], 0, s[12:13]
	global_store_dword v[50:51], v52, off
.LBB0_2818:
	s_or_b64 exec, exec, s[26:27]
	v_lshlrev_b32_e32 v52, 16, v220
	v_and_b32_e32 v53, 0xffff0000, v220
	v_lshlrev_b32_e32 v54, 16, v221
	v_and_b32_e32 v55, 0xffff0000, v221
	v_lshlrev_b32_e32 v56, 16, v222
	v_and_b32_e32 v57, 0xffff0000, v222
	v_pk_add_f32 v[46:47], v[46:47], v[52:53]
	v_pk_add_f32 v[48:49], v[48:49], v[54:55]
	v_pk_add_f32 v[54:55], v[42:43], v[56:57]
	v_cvt_pk_bf16_f32 v42, v46, v47
	v_mul_f32_e32 v47, v47, v47
	v_fmac_f32_e32 v47, v46, v46
	v_mul_f32_e32 v46, v49, v49
	v_fmac_f32_e32 v46, v48, v48
	v_lshlrev_b32_e32 v58, 16, v223
	v_and_b32_e32 v59, 0xffff0000, v223
	v_add_f32_e32 v46, v47, v46
	v_mul_f32_e32 v47, v55, v55
	v_pk_add_f32 v[52:53], v[44:45], v[58:59]
	v_fmac_f32_e32 v47, v54, v54
	v_add_f32_e32 v46, v47, v46
	v_mul_f32_e32 v47, v53, v53
	v_fmac_f32_e32 v47, v52, v52
	v_cvt_pk_bf16_f32 v43, v48, v49
	v_add_f32_e32 v56, v47, v46
	v_lshlrev_b32_e32 v46, 16, v224
	v_and_b32_e32 v47, 0xffff0000, v224
	v_lshlrev_b32_e32 v48, 16, v225
	v_and_b32_e32 v49, 0xffff0000, v225
	v_cvt_pk_bf16_f32 v44, v54, v55
	v_cvt_pk_bf16_f32 v45, v52, v53
	v_lshlrev_b32_e32 v52, 16, v226
	v_and_b32_e32 v53, 0xffff0000, v226
	v_pk_add_f32 v[40:41], v[40:41], v[48:49]
	v_pk_add_f32 v[38:39], v[38:39], v[46:47]
	v_pk_add_f32 v[48:49], v[34:35], v[52:53]
	v_mul_f32_e32 v34, v39, v39
	v_mul_f32_e32 v35, v41, v41
	v_fmac_f32_e32 v34, v38, v38
	v_fmac_f32_e32 v35, v40, v40
	v_lshlrev_b32_e32 v54, 16, v227
	v_and_b32_e32 v55, 0xffff0000, v227
	v_add_f32_e32 v34, v34, v35
	v_mul_f32_e32 v35, v49, v49
	v_pk_add_f32 v[46:47], v[36:37], v[54:55]
	v_fmac_f32_e32 v35, v48, v48
	v_add_f32_e32 v34, v35, v34
	v_mul_f32_e32 v35, v47, v47
	v_fmac_f32_e32 v35, v46, v46
	v_add_f32_e32 v34, v35, v34
	v_add_f32_e32 v37, v56, v34
	ds_bpermute_b32 v52, v179, v37
	s_waitcnt lgkmcnt(1)
	v_lshlrev_b64 v[50:51], 12, v[94:95]
	v_lshl_add_u64 v[34:35], v[50:51], 1, s[16:17]
	v_lshl_add_u64 v[50:51], v[174:175], 1, v[34:35]
	global_store_dwordx4 v[50:51], v[42:45], off
	s_waitcnt lgkmcnt(0)
	v_add_f32_e32 v34, v37, v52
	ds_bpermute_b32 v35, v114, v34
	v_cvt_pk_bf16_f32 v36, v38, v39
	v_cvt_pk_bf16_f32 v37, v40, v41
	v_cvt_pk_bf16_f32 v38, v48, v49
	v_cvt_pk_bf16_f32 v39, v46, v47
	global_store_dwordx4 v[50:51], v[36:39], off offset:256
	s_and_saveexec_b64 s[26:27], s[0:1]
	s_cbranch_execz .LBB0_2820
	s_lshl_b32 s12, s3, 4
	s_add_i32 s36, s12, s33
	s_ashr_i32 s37, s36, 31
	s_lshl_b64 s[36:37], s[36:37], 12
	s_waitcnt lgkmcnt(0)
	v_add_f32_e32 v36, v34, v35
	v_subrev_u32_e32 v34, s28, v94
	s_add_u32 s36, s8, s36
	v_ashrrev_i32_e32 v35, 31, v34
	s_addc_u32 s37, s9, s37
	v_lshl_add_u64 v[34:35], v[34:35], 4, s[36:37]
	s_lshl_b32 s12, s42, 2
	v_lshl_add_u64 v[34:35], v[34:35], 0, s[12:13]
	global_store_dword v[34:35], v36, off
.LBB0_2820:
	s_or_b64 exec, exec, s[26:27]
	v_lshlrev_b32_e32 v36, 16, v228
	v_and_b32_e32 v37, 0xffff0000, v228
	v_lshlrev_b32_e32 v38, 16, v229
	v_and_b32_e32 v39, 0xffff0000, v229
	v_lshlrev_b32_e32 v40, 16, v230
	v_and_b32_e32 v41, 0xffff0000, v230
	v_pk_add_f32 v[30:31], v[30:31], v[36:37]
	v_pk_add_f32 v[32:33], v[32:33], v[38:39]
	v_pk_add_f32 v[38:39], v[26:27], v[40:41]
	v_cvt_pk_bf16_f32 v26, v30, v31
	v_mul_f32_e32 v31, v31, v31
	v_fmac_f32_e32 v31, v30, v30
	v_mul_f32_e32 v30, v33, v33
	v_fmac_f32_e32 v30, v32, v32
	v_lshlrev_b32_e32 v42, 16, v231
	v_and_b32_e32 v43, 0xffff0000, v231
	v_add_f32_e32 v30, v31, v30
	v_mul_f32_e32 v31, v39, v39
	v_pk_add_f32 v[36:37], v[28:29], v[42:43]
	v_fmac_f32_e32 v31, v38, v38
	v_add_f32_e32 v30, v31, v30
	v_mul_f32_e32 v31, v37, v37
	v_fmac_f32_e32 v31, v36, v36
	v_cvt_pk_bf16_f32 v27, v32, v33
	v_add_f32_e32 v40, v31, v30
	v_lshlrev_b32_e32 v30, 16, v232
	v_and_b32_e32 v31, 0xffff0000, v232
	v_lshlrev_b32_e32 v32, 16, v233
	v_and_b32_e32 v33, 0xffff0000, v233
	v_cvt_pk_bf16_f32 v28, v38, v39
	v_cvt_pk_bf16_f32 v29, v36, v37
	v_lshlrev_b32_e32 v36, 16, v234
	v_and_b32_e32 v37, 0xffff0000, v234
	v_pk_add_f32 v[24:25], v[24:25], v[32:33]
	v_pk_add_f32 v[22:23], v[22:23], v[30:31]
	v_pk_add_f32 v[32:33], v[18:19], v[36:37]
	v_mul_f32_e32 v18, v23, v23
	v_mul_f32_e32 v19, v25, v25
	v_fmac_f32_e32 v18, v22, v22
	v_fmac_f32_e32 v19, v24, v24
	v_lshlrev_b32_e32 v38, 16, v235
	v_and_b32_e32 v39, 0xffff0000, v235
	v_add_f32_e32 v18, v18, v19
	v_mul_f32_e32 v19, v33, v33
	v_pk_add_f32 v[30:31], v[20:21], v[38:39]
	v_fmac_f32_e32 v19, v32, v32
	v_add_f32_e32 v18, v19, v18
	v_mul_f32_e32 v19, v31, v31
	v_fmac_f32_e32 v19, v30, v30
	v_add_f32_e32 v18, v19, v18
	v_add_f32_e32 v21, v40, v18
	ds_bpermute_b32 v36, v179, v21
	s_waitcnt lgkmcnt(1)
	v_lshlrev_b64 v[34:35], 12, v[92:93]
	v_lshl_add_u64 v[18:19], v[34:35], 1, s[16:17]
	v_lshl_add_u64 v[34:35], v[174:175], 1, v[18:19]
	global_store_dwordx4 v[34:35], v[26:29], off
	s_waitcnt lgkmcnt(0)
	v_add_f32_e32 v18, v21, v36
	ds_bpermute_b32 v19, v114, v18
	v_cvt_pk_bf16_f32 v20, v22, v23
	v_cvt_pk_bf16_f32 v21, v24, v25
	v_cvt_pk_bf16_f32 v22, v32, v33
	v_cvt_pk_bf16_f32 v23, v30, v31
	global_store_dwordx4 v[34:35], v[20:23], off offset:256
	s_and_saveexec_b64 s[26:27], s[0:1]
	s_cbranch_execz .LBB0_2822
	s_lshl_b32 s12, s3, 4
	s_add_i32 s36, s12, s33
	s_ashr_i32 s37, s36, 31
	s_lshl_b64 s[36:37], s[36:37], 12
	s_waitcnt lgkmcnt(0)
	v_add_f32_e32 v20, v18, v19
	v_subrev_u32_e32 v18, s28, v92
	s_add_u32 s36, s8, s36
	v_ashrrev_i32_e32 v19, 31, v18
	s_addc_u32 s37, s9, s37
	v_lshl_add_u64 v[18:19], v[18:19], 4, s[36:37]
	s_lshl_b32 s12, s42, 2
	v_lshl_add_u64 v[18:19], v[18:19], 0, s[12:13]
	global_store_dword v[18:19], v20, off
.LBB0_2822:
	s_or_b64 exec, exec, s[26:27]
	v_lshlrev_b32_e32 v20, 16, v236
	v_and_b32_e32 v21, 0xffff0000, v236
	v_lshlrev_b32_e32 v22, 16, v237
	v_and_b32_e32 v23, 0xffff0000, v237
	v_lshlrev_b32_e32 v24, 16, v238
	v_and_b32_e32 v25, 0xffff0000, v238
	v_pk_add_f32 v[14:15], v[14:15], v[20:21]
	v_pk_add_f32 v[16:17], v[16:17], v[22:23]
	v_pk_add_f32 v[22:23], v[10:11], v[24:25]
	v_cvt_pk_bf16_f32 v10, v14, v15
	v_mul_f32_e32 v15, v15, v15
	v_fmac_f32_e32 v15, v14, v14
	v_mul_f32_e32 v14, v17, v17
	v_fmac_f32_e32 v14, v16, v16
	v_lshlrev_b32_e32 v26, 16, v239
	v_and_b32_e32 v27, 0xffff0000, v239
	v_add_f32_e32 v14, v15, v14
	v_mul_f32_e32 v15, v23, v23
	v_pk_add_f32 v[20:21], v[12:13], v[26:27]
	v_fmac_f32_e32 v15, v22, v22
	v_add_f32_e32 v14, v15, v14
	v_mul_f32_e32 v15, v21, v21
	v_fmac_f32_e32 v15, v20, v20
	v_cvt_pk_bf16_f32 v11, v16, v17
	v_add_f32_e32 v24, v15, v14
	v_lshlrev_b32_e32 v14, 16, v240
	v_and_b32_e32 v15, 0xffff0000, v240
	v_lshlrev_b32_e32 v16, 16, v241
	v_and_b32_e32 v17, 0xffff0000, v241
	v_cvt_pk_bf16_f32 v12, v22, v23
	v_cvt_pk_bf16_f32 v13, v20, v21
	v_lshlrev_b32_e32 v20, 16, v242
	v_and_b32_e32 v21, 0xffff0000, v242
	v_pk_add_f32 v[8:9], v[8:9], v[16:17]
	v_pk_add_f32 v[6:7], v[6:7], v[14:15]
	v_pk_add_f32 v[16:17], v[2:3], v[20:21]
	v_mul_f32_e32 v2, v7, v7
	v_mul_f32_e32 v3, v9, v9
	v_fmac_f32_e32 v2, v6, v6
	v_fmac_f32_e32 v3, v8, v8
	v_lshlrev_b32_e32 v22, 16, v243
	v_and_b32_e32 v23, 0xffff0000, v243
	v_add_f32_e32 v2, v2, v3
	v_mul_f32_e32 v3, v17, v17
	v_pk_add_f32 v[14:15], v[4:5], v[22:23]
	v_fmac_f32_e32 v3, v16, v16
	v_add_f32_e32 v2, v3, v2
	v_mul_f32_e32 v3, v15, v15
	v_fmac_f32_e32 v3, v14, v14
	v_add_f32_e32 v2, v3, v2
	v_add_f32_e32 v5, v24, v2
	ds_bpermute_b32 v20, v179, v5
	s_waitcnt lgkmcnt(1)
	v_lshlrev_b64 v[18:19], 12, v[90:91]
	v_lshl_add_u64 v[2:3], v[18:19], 1, s[16:17]
	v_lshl_add_u64 v[18:19], v[174:175], 1, v[2:3]
	global_store_dwordx4 v[18:19], v[10:13], off
	s_waitcnt lgkmcnt(0)
	v_add_f32_e32 v2, v5, v20
	ds_bpermute_b32 v3, v114, v2
	v_cvt_pk_bf16_f32 v4, v6, v7
	v_cvt_pk_bf16_f32 v5, v8, v9
	v_cvt_pk_bf16_f32 v6, v16, v17
	v_cvt_pk_bf16_f32 v7, v14, v15
	global_store_dwordx4 v[18:19], v[4:7], off offset:256
	s_and_saveexec_b64 s[26:27], s[0:1]
	s_cbranch_execz .LBB0_2824
	s_lshl_b32 s3, s3, 4
	s_add_i32 s36, s3, s33
	s_ashr_i32 s37, s36, 31
	s_waitcnt lgkmcnt(0)
	v_add_f32_e32 v4, v2, v3
	v_subrev_u32_e32 v2, s28, v90
	s_lshl_b64 s[28:29], s[36:37], 12
	s_add_u32 s28, s8, s28
	v_ashrrev_i32_e32 v3, 31, v2
	s_addc_u32 s29, s9, s29
	v_lshl_add_u64 v[2:3], v[2:3], 4, s[28:29]
	s_lshl_b32 s12, s42, 2
	v_lshl_add_u64 v[2:3], v[2:3], 0, s[12:13]
	global_store_dword v[2:3], v4, off

	.amdhsa_kernel _Z9trunk_fwd4Args
		.amdhsa_group_segment_fixed_size 0
		.amdhsa_private_segment_fixed_size 0
		.amdhsa_kernarg_size 416
		.amdhsa_user_sgpr_count 2
		.amdhsa_user_sgpr_dispatch_ptr 0
		.amdhsa_user_sgpr_queue_ptr 0
		.amdhsa_user_sgpr_kernarg_segment_ptr 1
		.amdhsa_user_sgpr_dispatch_id 0
		.amdhsa_user_sgpr_kernarg_preload_length 0
		.amdhsa_user_sgpr_kernarg_preload_offset 0
		.amdhsa_user_sgpr_private_segment_size 0
		.amdhsa_uses_dynamic_stack 0
		.amdhsa_enable_private_segment 0
		.amdhsa_system_sgpr_workgroup_id_x 1
		.amdhsa_system_sgpr_workgroup_id_y 0
		.amdhsa_system_sgpr_workgroup_id_z 0
		.amdhsa_system_sgpr_workgroup_info 0
		.amdhsa_system_vgpr_workitem_id 0
		.amdhsa_next_free_vgpr 256
		.amdhsa_next_free_sgpr 102
		.amdhsa_accum_offset 256
		.amdhsa_reserve_vcc 1
		.amdhsa_float_round_mode_32 0
		.amdhsa_float_round_mode_16_64 0
		.amdhsa_float_denorm_mode_32 3
		.amdhsa_float_denorm_mode_16_64 3
		.amdhsa_dx10_clamp 1
		.amdhsa_ieee_mode 1
		.amdhsa_fp16_overflow 0
		.amdhsa_tg_split 0
		.amdhsa_exception_fp_ieee_invalid_op 0
		.amdhsa_exception_fp_denorm_src 0
		.amdhsa_exception_fp_ieee_div_zero 0
		.amdhsa_exception_fp_ieee_overflow 0
		.amdhsa_exception_fp_ieee_underflow 0
		.amdhsa_exception_fp_ieee_inexact 0
		.amdhsa_exception_int_div_zero 0
	.end_amdhsa_kernel

amdhsa.kernels:
  - .agpr_count:     0
    .args:
      - .offset:         0
        .size:           160
        .value_kind:     by_value
      - .offset:         160
        .size:           4
        .value_kind:     hidden_block_count_x
      - .offset:         164
        .size:           4
        .value_kind:     hidden_block_count_y
      - .offset:         168
        .size:           4
        .value_kind:     hidden_block_count_z
      - .offset:         172
        .size:           2
        .value_kind:     hidden_group_size_x
      - .offset:         174
        .size:           2
        .value_kind:     hidden_group_size_y
      - .offset:         176
        .size:           2
        .value_kind:     hidden_group_size_z
      - .offset:         178
        .size:           2
        .value_kind:     hidden_remainder_x
      - .offset:         180
        .size:           2
        .value_kind:     hidden_remainder_y
      - .offset:         182
        .size:           2
        .value_kind:     hidden_remainder_z
      - .offset:         200
        .size:           8
        .value_kind:     hidden_global_offset_x
      - .offset:         208
        .size:           8
        .value_kind:     hidden_global_offset_y
      - .offset:         216
        .size:           8
        .value_kind:     hidden_global_offset_z
      - .offset:         224
        .size:           2
        .value_kind:     hidden_grid_dims
      - .offset:         280
        .size:           4
        .value_kind:     hidden_dynamic_lds_size
    .group_segment_fixed_size: 0
    .kernarg_segment_align: 8
    .kernarg_segment_size: 416
    .language:       OpenCL C
    .language_version:
      - 2
      - 0
    .max_flat_workgroup_size: 512
    .name:           _Z9trunk_fwd4Args
    .private_segment_fixed_size: 0
    .sgpr_count:     108
    .sgpr_spill_count: 209
    .symbol:         _Z9trunk_fwd4Args.kd
    .uniform_work_group_size: 1
    .uses_dynamic_stack: false
    .vgpr_count:     256
    .vgpr_spill_count: 0
    .wavefront_size: 64
